# NSA far/near tile paths restructured; top-k rank loop skipped when every block is selected (i<16); SB query quarters reversed for waves 4-7 (SIMD partner balance)
# speedup vs baseline: 1.0174x; 1.0153x over previous
; #define LAS __attribute__((address_space(3)))
; __device__ __forceinline__ void sb_unit(const Params& p, LAS unsigned char* lds, int b, int hp, int qb, int tid, int lane, int wave) {
;     ...
;     const int col = lane & 31, hi = lane >> 5, w4 = wave & 3, hsel = wave >> 2, h = 2 * hp + hsel;
;     const int t = 128 * qb + 32 * w4 + col;
;     const size_t tok = (size_t)b * S + t;
;     const int tmaxw = 128 * qb + 32 * w4 + 31;
; __device__ __forceinline__ void phase4(const Params& p, LAS unsigned char* lds, int tid, int lane, int wave) {
;     for (int vb = blockIdx.x; vb < 256; vb += gridDim.x) {
;     const int v = (vb & 7) * 32 + (vb >> 3);
;     __syncthreads();
;     { const float* rel = p.in[2]; LAS float* lut = (LAS float*)(lds + LUT_OFF);
;       for (int e = tid; e < 1024; e += 512) { const int head = e >> 7, dist = e & 127;
;           int bk = dist; if (dist >= 16) { bk = 16 + (int)(logf((float)dist / 16.0f) / 2.0794415416798357f * 16.0f); bk = bk < 31 ? bk : 31; }
;           lut[e] = rel[bk * 8 + head] * LOG2E; } }
;     __syncthreads();
;     { const LAS float* lut = (const LAS float*)(lds + LUT_OFF); LAS float* l2 = (LAS float*)(lds + LUT2_OFF);
;       for (int e = tid; e < 8 * 260; e += 512) { const int head = e / 260, d = e % 260 - 68; l2[e] = d < 0 ? 0.f : lut[head * 128 + (d < 127 ? d : 127)]; } }
;     if (wave == 0) { const float* qg = p.in[13]; const float* kg = p.in[14]; LAS float* pm = (LAS float*)(lds + MISC4_OFF + 2304); const LAS float* lut = (const LAS float*)(lds + LUT_OFF);
.LBB0_428:
	s_or_b64 exec, exec, s[0:1]
	v_mov_b32_e32 v168, v218
	s_waitcnt lgkmcnt(0)
	s_barrier
	s_cmpk_gt_i32 s68, 0xff
	v_readfirstlane_b32 s0, v168
	s_cbranch_scc1 .LBB0_633
	v_writelane_b32 v251, s66, 30
	s_movk_i32 s1, 0x400
	v_cmp_gt_i32_e64 s[4:5], s1, v168
	v_writelane_b32 v251, s67, 31
	s_movk_i32 s1, 0x820
	v_writelane_b32 v251, s4, 32
	s_ashr_i32 s2, s0, 6
	s_cmp_lt_u32 s0, 64
	v_writelane_b32 v251, s5, 33
	v_cmp_gt_i32_e64 s[4:5], s1, v168
	v_and_b32_e32 v1, 63, v168
	v_lshlrev_b32_e32 v2, 2, v1
	v_writelane_b32 v251, s4, 34
	s_movk_i32 s36, 0x1ff
	s_mov_b32 s16, 0x41000000
	v_writelane_b32 v251, s5, 35
	s_cselect_b64 s[4:5], -1, 0
	v_writelane_b32 v251, s4, 36
	s_add_i32 s3, 0, 0x10000
	v_lshl_add_u32 v167, v1, 9, s3
	v_writelane_b32 v251, s5, 37
	v_cmp_gt_u32_e64 s[4:5], 8, v1
	s_ashr_i32 s0, s0, 8
	s_mov_b64 s[8:9], s[72:73]
	v_writelane_b32 v251, s4, 38
	s_mov_b64 s[20:21], s[84:85]
	v_lshlrev_b32_e32 v191, 2, v168
	v_writelane_b32 v251, s5, 39
	v_writelane_b32 v251, s3, 40
	s_add_i32 s3, 0, 0x21900
	v_writelane_b32 v251, s3, 41
	v_cmp_eq_u32_e64 s[4:5], 0, v1
	v_add_u32_e32 v171, s3, v2
	s_lshl_b32 s3, s2, 13
	v_writelane_b32 v251, s4, 42
	s_add_i32 s17, s3, 0
	s_lshl_b32 s3, s2, 10
	v_writelane_b32 v251, s5, 43
	s_lshl_b32 s4, s2, 3
	v_writelane_b32 v251, s3, 44
	s_add_i32 s92, s3, 0
	s_sub_i32 s3, s4, 31
	v_writelane_b32 v251, s3, 45
	s_lshl_b32 s3, s2, 8
	s_add_i32 s93, s3, 0
	s_add_i32 s3, s4, 0
	v_writelane_b32 v251, s4, 46
	s_add_i32 s3, s3, 0x21000
	v_writelane_b32 v251, s3, 47
	s_lshl_b32 s3, s2, 5
	s_and_b32 s3, s3, 0x60
	s_sub_i32 s98, 0x60, s3
	s_cmp_gt_u32 s2, 3
	s_cselect_b32 s3, s98, s3
	v_and_b32_e32 v1, 0x7f, v168
	v_writelane_b32 v251, s3, 48
	s_lshl_b32 s3, s0, 6
	s_lshl_b32 s0, s0, 14
	v_cvt_f32_ubyte0_e32 v3, v1
	s_add_i32 s31, s0, 0
	v_mul_f32_e32 v3, 0x3d800000, v3
	s_mov_b32 s0, 0x800000
	v_cmp_gt_f32_e32 vcc, s0, v3
	s_mov_b32 s0, 0x3f317217
	s_lshl_b32 s2, s2, 2
	v_cndmask_b32_e64 v4, 0, 32, vcc
	v_ldexp_f32 v3, v3, v4
	v_log_f32_e32 v3, v3
	s_add_i32 s2, s2, 0
	v_writelane_b32 v251, s3, 49
	s_add_i32 s30, s2, 0x21080
	v_mul_f32_e32 v4, 0x3f317217, v3
	v_fma_f32 v4, v3, s0, -v4
	v_fmamk_f32 v4, v3, 0x3377d1cf, v4
	s_mov_b32 s0, 0x7f800000
	v_fmac_f32_e32 v4, 0x3f317217, v3
	v_cmp_lt_f32_e64 s[12:13], |v3|, s0
	s_mov_b32 s0, 0x40051592
	v_cmp_lt_u32_e64 s[10:11], 15, v1
	v_cndmask_b32_e64 v3, v3, v4, s[12:13]
	v_mov_b32_e32 v4, 0x41b17218
	v_cndmask_b32_e32 v4, 0, v4, vcc
	v_sub_f32_e32 v3, v3, v4
	v_div_scale_f32 v4, s[2:3], s0, s0, v3
	v_rcp_f32_e32 v5, v4
	v_readlane_b32 s4, v251, 1
	s_add_i32 s17, s17, 0x11000
	s_add_i32 s33, s93, 0x21100
	v_fma_f32 v6, -v4, v5, 1.0
	v_fmac_f32_e32 v5, v6, v5
	v_div_scale_f32 v6, vcc, v3, s0, v3
	v_mul_f32_e32 v7, v6, v5
	v_fma_f32 v8, -v4, v7, v6
	v_fmac_f32_e32 v7, v8, v5
	v_fma_f32 v4, -v4, v7, v6
	v_div_fmas_f32 v4, v4, v5, v7
	v_div_fixup_f32 v3, v4, s0, v3
	v_mul_f32_e32 v3, 0x41800000, v3
	v_cvt_i32_f32_e32 v3, v3
	v_readlane_b32 s6, v251, 3
	v_readlane_b32 s7, v251, 4
	s_add_u32 s2, s6, 0x10200000
	v_min_i32_e32 v3, 15, v3
	v_add_u32_e32 v3, 16, v3
	v_cndmask_b32_e64 v1, v1, v3, s[10:11]
	v_lshlrev_b32_e32 v170, 3, v1
	v_max_i32_e32 v1, 0x200, v168
	v_sub_u32_e32 v1, v1, v168
	s_addc_u32 s3, s7, 0
	v_mov_b32_e32 v3, 0
	v_add_u32_e32 v1, 0x1ff, v1
	v_readlane_b32 s5, v251, 2
	v_writelane_b32 v251, s2, 50
	v_lshl_add_u64 v[172:173], s[22:23], 0, v[2:3]
	v_lshl_add_u64 v[174:175], s[24:25], 0, v[2:3]
	v_lshrrev_b32_e32 v2, 9, v1
	v_writelane_b32 v251, s3, 51
	v_add_u32_e32 v4, 1, v2
	v_add_u32_e32 v2, -1, v2
	v_cmp_lt_u32_e64 s[2:3], s36, v1
	v_lshrrev_b32_e32 v5, 1, v2
	v_add_u32_e32 v5, 1, v5
	v_writelane_b32 v251, s2, 52
	v_and_b32_e32 v189, 3, v5
	v_and_b32_e32 v6, 0xfffffe, v4
	v_writelane_b32 v251, s3, 53
	v_cmp_lt_u32_e64 s[2:3], 5, v2
	s_add_u32 s0, s6, 0x18298e00
	s_mov_b64 s[12:13], s[76:77]
	v_writelane_b32 v251, s2, 54
	v_add_u32_e32 v2, 0, v191
	s_mov_b32 s1, 0
	v_writelane_b32 v251, s3, 55
	v_cmp_ne_u32_e64 s[2:3], 0, v189
	v_lshl_add_u32 v177, v6, 9, v168
	v_mov_b32_e32 v1, v170
	v_writelane_b32 v251, s2, 56
	v_add_u32_e32 v169, 0x200, v168
	v_and_b32_e32 v190, -4, v5
	v_writelane_b32 v251, s3, 57
	v_cmp_ne_u32_e64 s[2:3], v4, v6
	v_add_u32_e32 v192, 0x10000, v2
	v_add_u32_e32 v193, 0x10800, v2
	v_writelane_b32 v251, s2, 58
	s_mov_b32 s40, 0x3fb8aa3b
	s_mov_b32 s94, 0xf149f2ca
	v_writelane_b32 v251, s3, 59
	v_writelane_b32 v251, s0, 60
	s_addc_u32 s0, s7, 0
	v_writelane_b32 v251, s0, 61
	s_lshl_b32 s0, s68, 2
	v_writelane_b32 v251, s0, 62
	v_writelane_b32 v251, s70, 63
	s_lshl_b32 s0, s70, 2
	v_mbcnt_hi_u32_b32 v194, -1, v188
	v_writelane_b32 v250, s71, 0
	v_writelane_b32 v250, s0, 1
	s_add_u32 s0, s6, 0x18038e00
	v_writelane_b32 v250, s0, 2
	s_addc_u32 s0, s7, 0
	v_writelane_b32 v250, s0, 3
	s_add_u32 s0, s6, 0x18039200
	v_writelane_b32 v250, s0, 4
	s_addc_u32 s0, s7, 0
	v_writelane_b32 v250, s0, 5
	s_add_i32 s0, 0, 0x21a00
	v_writelane_b32 v250, s0, 6
	s_add_i32 s0, 0, 0x21908
	v_writelane_b32 v250, s0, 7
	s_add_i32 s0, 0, 0x21010
	v_writelane_b32 v250, s0, 8
	s_add_i32 s0, 0, 0x21020
	v_writelane_b32 v250, s0, 9
	s_add_i32 s0, 0, 0x21030
	v_writelane_b32 v250, s0, 10
	v_writelane_b32 v250, s68, 11
	v_writelane_b32 v250, s68, 12
	v_writelane_b32 v250, s8, 13
	s_mov_b64 s[6:7], 0x80
	s_mov_b64 s[38:39], 0x2000
	v_writelane_b32 v250, s9, 14
	v_writelane_b32 v250, s10, 15
	v_writelane_b32 v250, s11, 16
	v_writelane_b32 v250, s12, 17
	v_writelane_b32 v250, s13, 18
	v_writelane_b32 v250, s14, 19
	v_writelane_b32 v250, s15, 20
	v_writelane_b32 v250, s16, 21
	v_writelane_b32 v250, s17, 22
	v_writelane_b32 v250, s18, 23
	v_writelane_b32 v250, s19, 24
	v_writelane_b32 v250, s20, 25
	v_writelane_b32 v250, s21, 26
	v_writelane_b32 v250, s22, 27
	v_writelane_b32 v250, s23, 28
	s_mov_b32 s95, 0xefa18f08
	v_mov_b32_e32 v195, 0x260
	s_mov_b32 s88, 0x3f803f80
	v_mov_b32_e32 v196, 0x7f
	v_mov_b32_e32 v197, 0xf149f2ca
	v_mov_b32_e32 v198, 0x461c4000
	v_mov_b32_e32 v199, 0xce6e6b28
	v_mov_b32_e32 v200, 0x98000
	v_writelane_b32 v250, s30, 29
	v_writelane_b32 v250, s31, 30
	s_branch .LBB0_431

; #define LAS __attribute__((address_space(3)))
; #define LDS_WAIT() asm volatile("s_waitcnt lgkmcnt(0)" ::: "memory")
; __device__ __forceinline__ void nsa_unit(const Params& p, LAS unsigned char* lds, int b, int hkv, int i, int tid, int lane, int wave) {
;     ...
;     unsigned long long mysel = 0ull, wsel = 0ull;
;     {
;         const unsigned long long curmask = (i == 63) ? ~0ull : ((1ull << (i + 1)) - 1ull);
;         const int want = i + 1 < 16 ? i + 1 : 16;
;         const int n = lane;
;         LAS float* vbuf = (LAS float*)(lds + MISC4_OFF + 256 + wave * 256);
;         for (int q = 0; q < 8; ++q) {
;             float v = impw[q * 64 + n] + (n > 0 ? impw3[q * 64 + n - 1] : 0.f) + ((n == 0 || n == i || n == i - 1) ? 1.0e4f : 0.f);
;             v = (n <= i) ? v : -1.0e9f;
;             vbuf[n] = v;
;             LDS_WAIT();
;             int cgt = 0;
; #pragma unroll
;             for (int m4 = 0; m4 < 16; ++m4) { const f32x4 w = *(const LAS f32x4*)(vbuf + 4 * m4); cgt += (w.x > v ? 1 : 0) + (w.y > v ? 1 : 0) + (w.z > v ? 1 : 0) + (w.w > v ? 1 : 0); }
;             LDS_WAIT();
;             unsigned long long sel = __ballot(cgt < 16) & curmask;
;             if (__builtin_popcountll(sel) != want) {
;                 int rank = 0;
; #pragma unroll 8
;                 for (int mm = 0; mm < 64; ++mm) { const float vm = vbuf[mm]; rank += (vm > v || (vm == v && mm < n)) ? 1 : 0; }
;                 LDS_WAIT();
;                 sel = __ballot(rank < 16) & curmask;
;             }
;             if (qp == q) mysel = sel;
;             wsel |= sel;
;         }
.LBB0_491:
	s_add_i32 s0, s67, 1
	s_lshl_b64 s[2:3], -1, s0
	s_not_b64 s[2:3], s[2:3]
	s_cmp_lg_u32 s67, 63
	s_cselect_b32 s3, s3, -1
	s_cselect_b32 s2, s2, -1
	s_add_i32 s5, s67, -1
	v_cmp_eq_u32_e32 vcc, 0, v124
	v_cmp_eq_u32_e64 s[20:21], s67, v124
	s_waitcnt lgkmcnt(0)
	s_or_b64 s[8:9], vcc, s[20:21]
	v_cmp_eq_u32_e64 s[20:21], s5, v124
	s_or_b64 s[20:21], s[8:9], s[20:21]
	s_min_i32 s0, s0, 16
	s_mov_b32 s4, 0
	v_cmp_ne_u32_e64 s[18:19], 0, v124
	v_cndmask_b32_e64 v4, 0, v198, s[20:21]
	v_cmp_lt_u32_e64 s[20:21], s67, v124
	v_lshl_add_u32 v6, v124, 2, s33
	v_mov_b32_e32 v5, v124
	v_mov_b64_e32 v[178:179], 0
	s_mov_b64 s[42:43], 0
	s_cmp_gt_u32 s67, 15
	s_cbranch_scc1 .LBB0_493
	v_mov_b32_e32 v178, s2
	v_mov_b32_e32 v179, s3
	s_mov_b64 s[42:43], s[2:3]
	s_branch .LBB0_499
